# P2 mask-free score blocks: pos_q-pos_k differences computed two at a time with v_pk_add_f32 (32 v_sub removed per tile pair), bit-identical
# speedup vs baseline: 1.0009x; 1.0009x over previous
.Lm_259:
	s_and_b32 s10, s33, 1
	s_mul_i32 s11, s10, 0x9100
	s_add_i32 s14, s11, 0
	v_add3_u32 v216, s14, v208, v178
	v_add_u32_e32 v96, v216, v209
	ds_read_b128 v[64:67], v96
	ds_read_b128 v[68:71], v96 offset:32
	ds_read_b128 v[72:75], v96 offset:64
	ds_read_b128 v[76:79], v96 offset:96
	s_add_i32 s40, s8, s9
	s_waitcnt lgkmcnt(3)
	v_mfma_f32_32x32x16_bf16 v[112:127], v[64:67], v[128:131], 0
	s_add_i32 s11, s40, 0x80
	s_addk_i32 s40, 0x107f
	v_lshl_add_u32 v224, v186, 2, s14
	s_waitcnt lgkmcnt(2)
	v_mfma_f32_32x32x16_bf16 v[112:127], v[68:71], v[132:135], v[112:127]
	v_mfma_f32_32x32x16_bf16 v[80:95], v[64:67], v[152:155], 0
	ds_read_b128 v[64:67], v96 offset:4608
	ds_read_b128 v[218:221], v96 offset:4640
	ds_read_b128 v[226:229], v96 offset:4672
	ds_read_b128 v[230:233], v96 offset:4704
	ds_read_b128 v[234:237], v224 offset:36880
	s_waitcnt lgkmcnt(0)
	v_pk_add_f32 v[246:247], v[200:201], v[234:235] op_sel:[1,0] op_sel_hi:[1,1] neg_lo:[0,1] neg_hi:[0,1]
	v_mfma_f32_32x32x16_bf16 v[112:127], v[72:75], v[136:139], v[112:127]
	v_mfma_f32_32x32x16_bf16 v[80:95], v[68:71], v[144:147], v[80:95]
	v_mfma_f32_32x32x16_bf16 v[112:127], v[76:79], v[140:143], v[112:127]
	v_mfma_f32_32x32x16_bf16 v[80:95], v[72:75], v[148:151], v[80:95]
	ds_read_b128 v[68:71], v224 offset:36864
	s_waitcnt lgkmcnt(0)
	v_pk_add_f32 v[248:249], v[200:201], v[68:69] op_sel:[1,0] op_sel_hi:[1,1] neg_lo:[0,1] neg_hi:[0,1]
	s_nop 5
	s_nop 1
	v_fma_f32 v217, -v207, |v248|, v112
	v_fma_f32 v113, -v207, |v249|, v113
	v_pk_add_f32 v[248:249], v[200:201], v[70:71] op_sel:[1,0] op_sel_hi:[1,1] neg_lo:[0,1] neg_hi:[0,1]
	v_fma_f32 v114, -v207, |v248|, v114
	v_max3_f32 v68, v217, s31, v113
	v_fma_f32 v115, -v207, |v249|, v115
	v_mfma_f32_32x32x16_bf16 v[80:95], v[76:79], v[156:159], v[80:95]
	v_fma_f32 v116, -v207, |v246|, v116
	v_max3_f32 v112, v68, v114, v115
	v_fma_f32 v117, -v207, |v247|, v117
	v_mfma_f32_32x32x16_bf16 v[96:111], v[64:67], v[128:131], 0
	v_mfma_f32_32x32x16_bf16 v[64:79], v[64:67], v[152:155], 0
	v_mfma_f32_32x32x16_bf16 v[96:111], v[218:221], v[132:135], v[96:111]
	v_mfma_f32_32x32x16_bf16 v[64:79], v[218:221], v[144:147], v[64:79]
	v_pk_add_f32 v[246:247], v[200:201], v[236:237] op_sel:[1,0] op_sel_hi:[1,1] neg_lo:[0,1] neg_hi:[0,1]
	v_fma_f32 v118, -v207, |v246|, v118
	v_mfma_f32_32x32x16_bf16 v[96:111], v[226:229], v[136:139], v[96:111]
	v_fma_f32 v119, -v207, |v247|, v119
	v_max3_f32 v112, v112, v116, v117
	v_mfma_f32_32x32x16_bf16 v[64:79], v[226:229], v[148:151], v[64:79]
	v_max3_f32 v112, v112, v118, v119
	v_mfma_f32_32x32x16_bf16 v[96:111], v[230:233], v[140:143], v[96:111]
	v_mfma_f32_32x32x16_bf16 v[64:79], v[230:233], v[156:159], v[64:79]
	ds_read_b128 v[218:221], v224 offset:36928
	ds_read_b128 v[226:229], v224 offset:36944
	s_waitcnt lgkmcnt(1)
	v_pk_add_f32 v[246:247], v[200:201], v[218:219] op_sel:[1,0] op_sel_hi:[1,1] neg_lo:[0,1] neg_hi:[0,1]
	v_fma_f32 v120, -v207, |v246|, v120
	v_pk_add_f32 v[248:249], v[200:201], v[220:221] op_sel:[1,0] op_sel_hi:[1,1] neg_lo:[0,1] neg_hi:[0,1]
	v_fma_f32 v121, -v207, |v247|, v121
	v_fma_f32 v122, -v207, |v248|, v122
	v_fma_f32 v123, -v207, |v249|, v123
	s_waitcnt lgkmcnt(0)
	v_pk_add_f32 v[246:247], v[200:201], v[226:227] op_sel:[1,0] op_sel_hi:[1,1] neg_lo:[0,1] neg_hi:[0,1]
	v_fma_f32 v124, -v207, |v246|, v124
	v_fma_f32 v125, -v207, |v247|, v125
	v_pk_add_f32 v[246:247], v[200:201], v[228:229] op_sel:[1,0] op_sel_hi:[1,1] neg_lo:[0,1] neg_hi:[0,1]
	v_fma_f32 v126, -v207, |v246|, v126
	v_max3_f32 v112, v112, v120, v121
	v_fma_f32 v127, -v207, |v247|, v127
	v_max3_f32 v112, v112, v122, v123
	v_max3_f32 v112, v112, v124, v125
	v_max3_f32 v112, v112, v126, v127
	ds_read_b128 v[218:221], v224 offset:36992
	ds_read_b128 v[226:229], v224 offset:37008
	s_waitcnt lgkmcnt(1)
	v_pk_add_f32 v[246:247], v[200:201], v[218:219] op_sel:[1,0] op_sel_hi:[1,1] neg_lo:[0,1] neg_hi:[0,1]
	v_fma_f32 v218, -v207, |v246|, v96
	v_fma_f32 v219, -v207, |v247|, v97
	v_pk_add_f32 v[246:247], v[200:201], v[220:221] op_sel:[1,0] op_sel_hi:[1,1] neg_lo:[0,1] neg_hi:[0,1]
	v_fma_f32 v220, -v207, |v246|, v98
	v_max3_f32 v96, v112, v218, v219
	v_fma_f32 v221, -v207, |v247|, v99
	s_waitcnt lgkmcnt(0)
	v_pk_add_f32 v[246:247], v[200:201], v[226:227] op_sel:[1,0] op_sel_hi:[1,1] neg_lo:[0,1] neg_hi:[0,1]
	v_fma_f32 v222, -v207, |v246|, v100
	v_max3_f32 v96, v96, v220, v221
	v_fma_f32 v223, -v207, |v247|, v101
	v_pk_add_f32 v[246:247], v[200:201], v[228:229] op_sel:[1,0] op_sel_hi:[1,1] neg_lo:[0,1] neg_hi:[0,1]
	v_fma_f32 v112, -v207, |v246|, v102
	v_max3_f32 v96, v96, v222, v223
	v_fma_f32 v103, -v207, |v247|, v103
	v_max3_f32 v100, v96, v112, v103
	ds_read_b128 v[96:99], v224 offset:37056
	ds_read_b128 v[226:229], v224 offset:37072
	s_waitcnt lgkmcnt(1)
	v_pk_add_f32 v[246:247], v[200:201], v[96:97] op_sel:[1,0] op_sel_hi:[1,1] neg_lo:[0,1] neg_hi:[0,1]
	v_fma_f32 v104, -v207, |v246|, v104
	v_fma_f32 v101, -v207, |v247|, v105
	v_pk_add_f32 v[246:247], v[200:201], v[98:99] op_sel:[1,0] op_sel_hi:[1,1] neg_lo:[0,1] neg_hi:[0,1]
	v_fma_f32 v102, -v207, |v246|, v106
	v_max3_f32 v97, v100, v104, v101
	v_fma_f32 v96, -v207, |v247|, v107
	v_max3_f32 v98, v97, v102, v96
	s_waitcnt lgkmcnt(0)
	v_pk_add_f32 v[246:247], v[200:201], v[226:227] op_sel:[1,0] op_sel_hi:[1,1] neg_lo:[0,1] neg_hi:[0,1]
	v_fma_f32 v97, -v207, |v246|, v108
	v_fma_f32 v99, -v207, |v247|, v109
	v_max3_f32 v105, v98, v97, v99
	v_pk_add_f32 v[246:247], v[200:201], v[228:229] op_sel:[1,0] op_sel_hi:[1,1] neg_lo:[0,1] neg_hi:[0,1]
	v_fma_f32 v98, -v207, |v246|, v110
	v_fma_f32 v100, -v207, |v247|, v111
	v_max3_f32 v105, v105, v98, v100
	v_sub_f32_e32 v106, v105, v214
	v_cmp_lt_f32_e32 vcc, s34, v106
	s_cbranch_vccnz .Lm_263
.Lm_260:
	ds_read_b128 v[106:109], v224 offset:36864
	ds_read_b128 v[230:233], v224 offset:36880
	s_waitcnt lgkmcnt(1)
	v_pk_add_f32 v[246:247], v[202:203], v[106:107] op_sel:[1,0] op_sel_hi:[1,1] neg_lo:[0,1] neg_hi:[0,1]
	v_fma_f32 v225, -v207, |v246|, v80
	v_fma_f32 v226, -v207, |v247|, v81
	v_pk_add_f32 v[246:247], v[202:203], v[108:109] op_sel:[1,0] op_sel_hi:[1,1] neg_lo:[0,1] neg_hi:[0,1]
	v_fma_f32 v227, -v207, |v246|, v82
	v_max3_f32 v80, v225, s31, v226
	v_fma_f32 v228, -v207, |v247|, v83
	s_waitcnt lgkmcnt(0)
	v_pk_add_f32 v[246:247], v[202:203], v[230:231] op_sel:[1,0] op_sel_hi:[1,1] neg_lo:[0,1] neg_hi:[0,1]
	v_fma_f32 v229, -v207, |v246|, v84
	v_max3_f32 v80, v80, v227, v228
	v_fma_f32 v230, -v207, |v247|, v85
	v_pk_add_f32 v[246:247], v[202:203], v[232:233] op_sel:[1,0] op_sel_hi:[1,1] neg_lo:[0,1] neg_hi:[0,1]
	v_fma_f32 v231, -v207, |v246|, v86
	v_max3_f32 v80, v80, v229, v230
	v_fma_f32 v232, -v207, |v247|, v87
	v_max3_f32 v81, v80, v231, v232
	ds_read_b128 v[82:85], v224 offset:36928
	ds_read_b128 v[106:109], v224 offset:36944
	s_waitcnt lgkmcnt(1)
	v_pk_add_f32 v[246:247], v[202:203], v[82:83] op_sel:[1,0] op_sel_hi:[1,1] neg_lo:[0,1] neg_hi:[0,1]
	v_fma_f32 v82, -v207, |v246|, v88
	v_fma_f32 v80, -v207, |v247|, v89
	v_pk_add_f32 v[246:247], v[202:203], v[84:85] op_sel:[1,0] op_sel_hi:[1,1] neg_lo:[0,1] neg_hi:[0,1]
	v_fma_f32 v83, -v207, |v246|, v90
	v_fma_f32 v86, -v207, |v247|, v91
	v_max3_f32 v81, v81, v82, v80
	s_waitcnt lgkmcnt(0)
	v_pk_add_f32 v[246:247], v[202:203], v[106:107] op_sel:[1,0] op_sel_hi:[1,1] neg_lo:[0,1] neg_hi:[0,1]
	v_fma_f32 v88, -v207, |v246|, v92
	v_max3_f32 v81, v81, v83, v86
	v_fma_f32 v90, -v207, |v247|, v93
	v_pk_add_f32 v[246:247], v[202:203], v[108:109] op_sel:[1,0] op_sel_hi:[1,1] neg_lo:[0,1] neg_hi:[0,1]
	v_fma_f32 v92, -v207, |v246|, v94
	v_max3_f32 v81, v81, v88, v90
	v_fma_f32 v94, -v207, |v247|, v95
	v_max3_f32 v85, v81, v92, v94
	ds_read_b128 v[106:109], v224 offset:36992
	ds_read_b128 v[234:237], v224 offset:37008
	s_waitcnt lgkmcnt(1)
	v_pk_add_f32 v[246:247], v[202:203], v[106:107] op_sel:[1,0] op_sel_hi:[1,1] neg_lo:[0,1] neg_hi:[0,1]
	v_fma_f32 v84, -v207, |v246|, v64
	v_fma_f32 v81, -v207, |v247|, v65
	v_pk_add_f32 v[246:247], v[202:203], v[108:109] op_sel:[1,0] op_sel_hi:[1,1] neg_lo:[0,1] neg_hi:[0,1]
	v_fma_f32 v65, -v207, |v246|, v66
	v_max3_f32 v64, v85, v84, v81
	v_mov_b32_e32 v85, v65
	v_fma_f32 v87, -v207, |v247|, v67
	s_waitcnt lgkmcnt(0)
	v_pk_add_f32 v[246:247], v[202:203], v[234:235] op_sel:[1,0] op_sel_hi:[1,1] neg_lo:[0,1] neg_hi:[0,1]
	v_fma_f32 v89, -v207, |v246|, v68
	v_max3_f32 v64, v64, v85, v87
	v_fma_f32 v91, -v207, |v247|, v69
	v_pk_add_f32 v[246:247], v[202:203], v[236:237] op_sel:[1,0] op_sel_hi:[1,1] neg_lo:[0,1] neg_hi:[0,1]
	v_fma_f32 v93, -v207, |v246|, v70
	v_max3_f32 v64, v64, v89, v91
	v_fma_f32 v95, -v207, |v247|, v71
	v_max3_f32 v106, v64, v93, v95
	ds_read_b128 v[64:67], v224 offset:37056
	ds_read_b128 v[68:71], v224 offset:37072
	s_waitcnt lgkmcnt(1)
	v_pk_add_f32 v[246:247], v[202:203], v[64:65] op_sel:[1,0] op_sel_hi:[1,1] neg_lo:[0,1] neg_hi:[0,1]
	v_fma_f32 v64, -v207, |v246|, v72
	v_fma_f32 v65, -v207, |v247|, v73
	v_pk_add_f32 v[246:247], v[202:203], v[66:67] op_sel:[1,0] op_sel_hi:[1,1] neg_lo:[0,1] neg_hi:[0,1]
	v_fma_f32 v66, -v207, |v246|, v74
	v_fma_f32 v67, -v207, |v247|, v75
	s_waitcnt lgkmcnt(0)
	v_pk_add_f32 v[246:247], v[202:203], v[68:69] op_sel:[1,0] op_sel_hi:[1,1] neg_lo:[0,1] neg_hi:[0,1]
	v_fma_f32 v68, -v207, |v246|, v76
	v_fma_f32 v69, -v207, |v247|, v77
	v_pk_add_f32 v[246:247], v[202:203], v[70:71] op_sel:[1,0] op_sel_hi:[1,1] neg_lo:[0,1] neg_hi:[0,1]
	v_max3_f32 v72, v106, v64, v65
	v_fma_f32 v70, -v207, |v246|, v78
	v_max3_f32 v72, v72, v66, v67
	v_fma_f32 v71, -v207, |v247|, v79
	v_max3_f32 v72, v72, v68, v69
	v_max3_f32 v72, v72, v70, v71
	v_sub_f32_e32 v73, v72, v215
	v_cmp_lt_f32_e32 vcc, s34, v73
	s_cbranch_vccnz .LBB0_264
	s_branch .LBB0_261
